# s3 item: decay-matrix block with batched ds_read_b128 + cndmask instead of per-element exec-masked chains; d_skip fetched by scalar loads once per item so the per-head prefetch is no longer drained by
# baseline (speedup 1.0000x reference)
.LBB0_185:
	s_or_b64 exec, exec, s[12:13]
	s_movk_i32 s12, 0x1400
	s_waitcnt lgkmcnt(0)
	v_mad_u64_u32 v[76:77], s[10:11], v98, s12, 0
	v_readlane_b32 s10, v254, 24
	v_readlane_b32 s11, v254, 25
	v_add_u32_e32 v133, v81, v121
	v_mad_i32_i24 v77, v99, s12, v77
	v_cndmask_b32_e64 v2, 0, 1, s[10:11]
	v_lshlrev_b32_e32 v0, 9, v2
	v_readfirstlane_b32 s10, v2
	s_lshl_b32 s25, s10, 2
	v_readlane_b32 s10, v253, 58
	s_add_i32 s10, s10, s25
	s_ashr_i32 s11, s10, 31
	s_lshl_b64 s[38:39], s[10:11], 2
	v_lshrrev_b32_e32 v2, 5, v102
	v_readlane_b32 s11, v253, 35
	v_and_b32_e32 v78, 12, v2
	v_readlane_b32 s10, v253, 34
	v_lshl_add_u32 v95, v107, 1, s11
	v_add_u32_e32 v81, s11, v120
	s_mov_b32 s11, 0xfffffe0
	v_lshl_add_u32 v93, v105, 1, s10
	v_lshrrev_b32_e32 v3, 3, v102
	v_add_u32_e32 v98, s10, v120
	v_and_or_b32 v99, v104, s11, v78
	s_movk_i32 s10, 0x110
	v_and_or_b32 v78, v106, s11, v78
	v_and_b32_e32 v3, 16, v3
	v_mul_lo_u32 v104, v78, s10
	v_and_b32_e32 v78, 0xfffffe0, v88
	v_lshrrev_b32_e32 v88, 6, v102
	v_and_or_b32 v79, v2, 3, v3
	v_and_b32_e32 v88, 12, v88
	v_or3_b32 v78, v78, v88, v79
	v_mul_lo_u32 v102, v78, s10
	v_and_b32_e32 v78, 0xfffffe0, v90
	v_lshrrev_b32_e32 v90, 6, v103
	v_and_b32_e32 v90, 12, v90
	v_or3_b32 v78, v78, v90, v79
	v_mul_lo_u32 v90, v78, s10
	v_and_b32_e32 v78, 0xfffffe0, v92
	v_readlane_b32 s12, v254, 9
	v_or3_b32 v78, v88, v78, v79
	v_lshrrev_b32_e32 v91, 6, v91
	v_mov_b32_e32 v97, v1
	v_readlane_b32 s13, v254, 10
	v_mul_lo_u32 v88, v78, s10
	v_and_b32_e32 v78, 0xfffffe0, v94
	v_and_b32_e32 v91, 12, v91
	v_lshl_add_u64 v[2:3], s[12:13], 0, v[96:97]
	v_lshlrev_b32_e32 v97, 2, v89
	v_or3_b32 v78, v78, v91, v79
	v_mul_lo_u32 v91, v78, s10
	v_or_b32_e32 v78, 2, v97
	v_cmp_le_i32_e64 s[14:15], v78, v80
	v_or_b32_e32 v78, 3, v97
	v_cmp_le_i32_e64 s[16:17], v78, v80
	v_or_b32_e32 v78, 16, v97
	v_cmp_le_i32_e64 s[18:19], v78, v80
	v_or_b32_e32 v78, 17, v97
	v_cmp_le_i32_e64 s[40:41], v78, v80
	v_or_b32_e32 v78, 18, v97
	v_cmp_le_i32_e64 s[42:43], v78, v80
	v_or_b32_e32 v78, 19, v97
	v_cmp_le_i32_e64 s[44:45], v78, v80
	v_or_b32_e32 v78, 32, v97
	v_cmp_le_i32_e64 s[48:49], v78, v80
	v_or_b32_e32 v78, 33, v97
	v_cmp_le_i32_e64 s[50:51], v78, v80
	v_or_b32_e32 v78, 34, v97
	v_cmp_le_i32_e64 s[52:53], v78, v80
	v_or_b32_e32 v78, 35, v97
	v_cmp_le_i32_e64 s[54:55], v78, v80
	v_or_b32_e32 v78, 48, v97
	v_cmp_le_i32_e64 s[58:59], v78, v80
	v_or_b32_e32 v78, 49, v97
	v_cmp_le_i32_e64 s[60:61], v78, v80
	v_or_b32_e32 v78, 50, v97
	v_cmp_le_i32_e64 s[62:63], v78, v80
	v_or_b32_e32 v78, 51, v97
	v_cmp_le_i32_e64 s[64:65], v78, v80
	v_or_b32_e32 v78, 64, v97
	v_cmp_le_i32_e64 s[68:69], v78, v80
	v_or_b32_e32 v78, 0x41, v97
	v_cmp_le_i32_e64 s[70:71], v78, v80
	v_or_b32_e32 v78, 0x42, v97
	v_cmp_le_i32_e64 s[72:73], v78, v80
	v_or_b32_e32 v78, 0x43, v97
	v_cmp_le_i32_e64 s[74:75], v78, v80
	v_or_b32_e32 v78, 0x50, v97
	v_cmp_le_i32_e64 s[78:79], v78, v80
	v_or_b32_e32 v78, 0x51, v97
	v_cmp_le_i32_e64 s[80:81], v78, v80
	v_or_b32_e32 v78, 0x52, v97
	v_cmp_le_i32_e64 s[82:83], v78, v80
	v_or_b32_e32 v78, 0x53, v97
	v_cmp_le_i32_e64 s[84:85], v78, v80
	v_or_b32_e32 v78, 0x60, v97
	v_cmp_le_i32_e64 s[88:89], v78, v80
	v_or_b32_e32 v78, 0x61, v97
	v_cmp_le_i32_e64 s[90:91], v78, v80
	v_or_b32_e32 v78, 0x62, v97
	v_cmp_le_i32_e64 s[92:93], v78, v80
	v_or_b32_e32 v78, 0x63, v97
	v_cmp_le_i32_e64 s[94:95], v78, v80
	v_or_b32_e32 v78, 0x70, v97
	v_mul_lo_u32 v99, v99, s10
	v_cmp_le_i32_e64 s[10:11], v97, v80
	v_cmp_le_i32_e64 s[20:21], v78, v80
	v_or_b32_e32 v78, 0x71, v97
	v_writelane_b32 v254, s10, 18
	v_cmp_le_i32_e64 s[22:23], v78, v80
	v_lshlrev_b32_e32 v78, 2, v101
	v_writelane_b32 v254, s11, 19
	v_lshl_or_b32 v78, v100, 6, v78
	s_add_i32 s10, 0, 0x19800
	v_add_u32_e32 v135, s10, v78
	v_lshl_add_u64 v[78:79], v[82:83], 0, v[0:1]
	v_readlane_b32 s28, v253, 46
	v_lshl_add_u64 v[82:83], v[84:85], 1, v[78:79]
	v_readlane_b32 s29, v253, 47
	v_lshl_add_u64 v[78:79], v[86:87], 1, v[78:79]
	v_or_b32_e32 v0, v0, v120
	v_readlane_b32 s10, v254, 20
	v_lshl_add_u64 v[124:125], s[28:29], 0, v[78:79]
	v_lshl_add_u64 v[78:79], v[118:119], 0, v[0:1]
	v_readlane_b32 s11, v254, 21
	s_waitcnt lgkmcnt(0)
	s_barrier
	v_lshl_add_u64 v[76:77], v[76:77], 0, v[0:1]
	v_lshl_add_u64 v[126:127], s[10:11], 0, v[78:79]
	v_readlane_b32 s10, v254, 22
	v_readlane_b32 s11, v254, 23
	v_or_b32_e32 v96, 1, v100
	v_or_b32_e32 v92, 0x72, v97
	v_or_b32_e32 v94, 0x73, v97
	v_lshl_add_u64 v[128:129], s[10:11], 0, v[76:77]
	s_add_i32 s10, s24, s25
	v_cmp_lt_i32_e64 s[12:13], v97, v80
	v_cmp_lt_i32_e64 s[46:47], 1, v96
	v_cmp_lt_i32_e64 s[56:57], 2, v96
	v_cmp_lt_i32_e64 s[66:67], 3, v96
	v_cmp_lt_i32_e64 s[76:77], 4, v96
	v_cmp_lt_i32_e64 s[86:87], 5, v96
	v_cmp_lt_i32_e64 s[96:97], 6, v96
	v_lshl_add_u32 v134, v89, 4, 0
	v_lshl_add_u64 v[122:123], s[28:29], 0, v[82:83]
	v_lshl_add_u64 v[130:131], s[28:29], 0, v[78:79]
	s_add_i32 s36, s10, 1
	v_mov_b32_e32 v144, 0
	s_mov_b32 s33, 0
	v_add_u32_e32 v136, v93, v99
	v_add_u32_e32 v137, v93, v104
	v_add_u32_e32 v138, v95, v102
	v_add_u32_e32 v139, v95, v90
	v_add_u32_e32 v140, v95, v88
	v_add_u32_e32 v141, v95, v91
	v_add_u32_e32 v142, v81, v143
	v_add_u32_e32 v143, v98, v143
	v_cmp_le_i32_e64 s[24:25], v92, v80
	v_cmp_le_i32_e64 s[26:27], v94, v80
	s_mov_b64 s[34:35], 0
	v_readlane_b32 s30, v253, 48
	v_readlane_b32 s31, v253, 49
	v_readlane_b32 s40, v253, 42
	v_readlane_b32 s41, v253, 43
	s_nop 0
	s_load_dwordx2 s[40:41], s[40:41], 0x98
	s_waitcnt lgkmcnt(0)
	s_add_u32 s40, s40, s38
	s_addc_u32 s41, s41, s39
	s_load_dwordx4 s[40:43], s[40:41], 0x0
	s_waitcnt lgkmcnt(0)
.LBB0_186:
	v_cvt_pk_bf16_f32 v76, v12, v13
	v_cvt_pk_bf16_f32 v77, v14, v15
	ds_write_b16 v136, v4
	ds_write_b16_d16_hi v136, v4 offset:272
	ds_write_b16 v136, v5 offset:544
	ds_write_b16_d16_hi v136, v5 offset:816
	ds_write_b16 v136, v6 offset:4352
	ds_write_b16_d16_hi v136, v6 offset:4624
	ds_write_b16 v136, v7 offset:4896
	ds_write_b16_d16_hi v136, v7 offset:5168
	ds_write_b16 v137, v8
	ds_write_b16_d16_hi v137, v8 offset:272
	ds_write_b16 v137, v9 offset:544
	ds_write_b16_d16_hi v137, v9 offset:816
	ds_write_b16 v137, v10 offset:4352
	ds_write_b16_d16_hi v137, v10 offset:4624
	ds_write_b16 v137, v11 offset:4896
	ds_write_b16_d16_hi v137, v11 offset:5168
	ds_write_b64 v138, v[76:77]
	v_cvt_pk_bf16_f32 v76, v16, v17
	v_cvt_pk_bf16_f32 v77, v18, v19
	ds_write_b64 v139, v[76:77]
	v_cvt_pk_bf16_f32 v76, v20, v21
	v_cvt_pk_bf16_f32 v77, v22, v23
	ds_write_b64 v140, v[76:77]
	v_cvt_pk_bf16_f32 v76, v24, v25
	v_cvt_pk_bf16_f32 v77, v26, v27
	ds_write_b64 v141, v[76:77]
	s_cmpk_eq_i32 s33, 0x600
	v_mov_b64_e32 v[84:85], v[68:69]
	v_mov_b64_e32 v[86:87], v[70:71]
	v_mov_b64_e32 v[88:89], v[28:29]
	v_mov_b64_e32 v[90:91], v[30:31]
	v_mov_b64_e32 v[76:77], v[72:73]
	v_mov_b64_e32 v[78:79], v[74:75]
	v_mov_b64_e32 v[80:81], v[32:33]
	v_mov_b64_e32 v[82:83], v[34:35]
	s_cbranch_scc0 .LBB0_194
	v_add_u32_e32 v0, s33, v135
	ds_read_b32 v0, v0
	s_branch .Ls3m_go

.Ls3m_go:
	s_mov_b64 s[28:29], exec
	v_lshrrev_b32_e32 v154, 6, v201
	v_readfirstlane_b32 s98, v154
	v_add_u32_e32 v155, s33, v134
	v_add_u32_e32 v155, 0x19800, v155
	v_and_b32_e32 v156, 15, v201
	v_lshl_add_u32 v156, v154, 4, v156
	v_bfe_u32 v157, v201, 4, 2
	v_lshlrev_b32_e32 v157, 2, v157
	v_sub_u32_e32 v156, v156, v157
	ds_read_b128 v[158:161], v155
	ds_read_b128 v[162:165], v155 offset:2048
	ds_read_b128 v[166:169], v155 offset:64
	ds_read_b128 v[170:173], v155 offset:2112
	s_cmp_lt_u32 s98, 2
	s_cbranch_scc1 .Ls3m_rd
	ds_read_b128 v[174:177], v155 offset:128
	ds_read_b128 v[178:181], v155 offset:2176
	ds_read_b128 v[182:185], v155 offset:192
	ds_read_b128 v[186:189], v155 offset:2240
	s_cmp_lt_u32 s98, 4
	s_cbranch_scc1 .Ls3m_rd
	ds_read_b128 v[190:193], v155 offset:256
	ds_read_b128 v[196:199], v155 offset:2304
	ds_read_b128 v[202:205], v155 offset:320
	ds_read_b128 v[206:209], v155 offset:2368
	s_cmp_lt_u32 s98, 6
	s_cbranch_scc1 .Ls3m_rd
	ds_read_b128 v[210:213], v155 offset:384
	ds_read_b128 v[214:217], v155 offset:2432
	ds_read_b128 v[218:221], v155 offset:448
	ds_read_b128 v[222:225], v155 offset:2496
.Ls3m_rd:
	s_waitcnt lgkmcnt(0)
	v_mov_b32_e32 v157, v156
	v_sub_f32_e32 v226, v0, v158
	v_sub_f32_e32 v227, v0, v159
	v_sub_f32_e32 v228, v0, v160
	v_sub_f32_e32 v229, v0, v161
	v_mul_f32_e32 v226, 0x3fb8aa3b, v226
	v_mul_f32_e32 v227, 0x3fb8aa3b, v227
	v_mul_f32_e32 v228, 0x3fb8aa3b, v228
	v_mul_f32_e32 v229, 0x3fb8aa3b, v229
	v_exp_f32_e32 v226, v226
	v_exp_f32_e32 v227, v227
	v_exp_f32_e32 v228, v228
	v_exp_f32_e32 v229, v229
	v_mul_f32_e32 v226, v36, v226
	v_mul_f32_e32 v227, v37, v227
	v_mul_f32_e32 v228, v38, v228
	v_mul_f32_e32 v229, v39, v229
	v_mul_f32_e32 v226, v162, v226
	v_mul_f32_e32 v227, v163, v227
	v_mul_f32_e32 v228, v164, v228
	v_mul_f32_e32 v229, v165, v229
	v_cmp_le_i32_e64 s[10:11], 0, v157
	v_cmp_le_i32_e64 s[30:31], 1, v157
	v_cmp_le_i32_e64 s[100:101], 2, v157
	v_cndmask_b32_e64 v226, 0, v226, s[10:11]
	v_cndmask_b32_e64 v227, 0, v227, s[30:31]
	v_cmp_le_i32_e64 s[10:11], 3, v157
	v_cndmask_b32_e64 v228, 0, v228, s[100:101]
	s_nop 1
	v_cndmask_b32_e64 v229, 0, v229, s[10:11]
	v_cvt_pk_bf16_f32 v230, v226, v227
	v_cvt_pk_bf16_f32 v231, v228, v229
	ds_write_b64 v133, v[230:231] offset:34816
	v_add_u32_e32 v157, -16, v156
	v_sub_f32_e32 v226, v0, v166
	v_sub_f32_e32 v227, v0, v167
	v_sub_f32_e32 v228, v0, v168
	v_sub_f32_e32 v229, v0, v169
	v_mul_f32_e32 v226, 0x3fb8aa3b, v226
	v_mul_f32_e32 v227, 0x3fb8aa3b, v227
	v_mul_f32_e32 v228, 0x3fb8aa3b, v228
	v_mul_f32_e32 v229, 0x3fb8aa3b, v229
	v_exp_f32_e32 v226, v226
	v_exp_f32_e32 v227, v227
	v_exp_f32_e32 v228, v228
	v_exp_f32_e32 v229, v229
	v_mul_f32_e32 v226, v40, v226
	v_mul_f32_e32 v227, v41, v227
	v_mul_f32_e32 v228, v42, v228
	v_mul_f32_e32 v229, v43, v229
	v_mul_f32_e32 v226, v170, v226
	v_mul_f32_e32 v227, v171, v227
	v_mul_f32_e32 v228, v172, v228
	v_mul_f32_e32 v229, v173, v229
	v_cmp_le_i32_e64 s[10:11], 0, v157
	v_cmp_le_i32_e64 s[30:31], 1, v157
	v_cmp_le_i32_e64 s[100:101], 2, v157
	v_cndmask_b32_e64 v226, 0, v226, s[10:11]
	v_cndmask_b32_e64 v227, 0, v227, s[30:31]
	v_cmp_le_i32_e64 s[10:11], 3, v157
	v_cndmask_b32_e64 v228, 0, v228, s[100:101]
	s_nop 1
	v_cndmask_b32_e64 v229, 0, v229, s[10:11]
	v_cvt_pk_bf16_f32 v232, v226, v227
	v_cvt_pk_bf16_f32 v233, v228, v229
	ds_write_b64 v133, v[232:233] offset:34848
	s_cmp_lt_u32 s98, 2
	s_cbranch_scc1 .Ls3m_cd
	v_add_u32_e32 v157, -32, v156
	v_sub_f32_e32 v226, v0, v174
	v_sub_f32_e32 v227, v0, v175
	v_sub_f32_e32 v228, v0, v176
	v_sub_f32_e32 v229, v0, v177
	v_mul_f32_e32 v226, 0x3fb8aa3b, v226
	v_mul_f32_e32 v227, 0x3fb8aa3b, v227
	v_mul_f32_e32 v228, 0x3fb8aa3b, v228
	v_mul_f32_e32 v229, 0x3fb8aa3b, v229
	v_exp_f32_e32 v226, v226
	v_exp_f32_e32 v227, v227
	v_exp_f32_e32 v228, v228
	v_exp_f32_e32 v229, v229
	v_mul_f32_e32 v226, v44, v226
	v_mul_f32_e32 v227, v45, v227
	v_mul_f32_e32 v228, v46, v228
	v_mul_f32_e32 v229, v47, v229
	v_mul_f32_e32 v226, v178, v226
	v_mul_f32_e32 v227, v179, v227
	v_mul_f32_e32 v228, v180, v228
	v_mul_f32_e32 v229, v181, v229
	v_cmp_le_i32_e64 s[10:11], 0, v157
	v_cmp_le_i32_e64 s[30:31], 1, v157
	v_cmp_le_i32_e64 s[100:101], 2, v157
	v_cndmask_b32_e64 v226, 0, v226, s[10:11]
	v_cndmask_b32_e64 v227, 0, v227, s[30:31]
	v_cmp_le_i32_e64 s[10:11], 3, v157
	v_cndmask_b32_e64 v228, 0, v228, s[100:101]
	s_nop 1
	v_cndmask_b32_e64 v229, 0, v229, s[10:11]
	v_cvt_pk_bf16_f32 v230, v226, v227
	v_cvt_pk_bf16_f32 v231, v228, v229
	ds_write_b64 v133, v[230:231] offset:34880
	v_add_u32_e32 v157, -48, v156
	v_sub_f32_e32 v226, v0, v182
	v_sub_f32_e32 v227, v0, v183
	v_sub_f32_e32 v228, v0, v184
	v_sub_f32_e32 v229, v0, v185
	v_mul_f32_e32 v226, 0x3fb8aa3b, v226
	v_mul_f32_e32 v227, 0x3fb8aa3b, v227
	v_mul_f32_e32 v228, 0x3fb8aa3b, v228
	v_mul_f32_e32 v229, 0x3fb8aa3b, v229
	v_exp_f32_e32 v226, v226
	v_exp_f32_e32 v227, v227
	v_exp_f32_e32 v228, v228
	v_exp_f32_e32 v229, v229
	v_mul_f32_e32 v226, v48, v226
	v_mul_f32_e32 v227, v49, v227
	v_mul_f32_e32 v228, v50, v228
	v_mul_f32_e32 v229, v51, v229
	v_mul_f32_e32 v226, v186, v226
	v_mul_f32_e32 v227, v187, v227
	v_mul_f32_e32 v228, v188, v228
	v_mul_f32_e32 v229, v189, v229
	v_cmp_le_i32_e64 s[10:11], 0, v157
	v_cmp_le_i32_e64 s[30:31], 1, v157
	v_cmp_le_i32_e64 s[100:101], 2, v157
	v_cndmask_b32_e64 v226, 0, v226, s[10:11]
	v_cndmask_b32_e64 v227, 0, v227, s[30:31]
	v_cmp_le_i32_e64 s[10:11], 3, v157
	v_cndmask_b32_e64 v228, 0, v228, s[100:101]
	s_nop 1
	v_cndmask_b32_e64 v229, 0, v229, s[10:11]
	v_cvt_pk_bf16_f32 v232, v226, v227
	v_cvt_pk_bf16_f32 v233, v228, v229
	ds_write_b64 v133, v[232:233] offset:34912
	s_cmp_lt_u32 s98, 4
	s_cbranch_scc1 .Ls3m_cd
	v_add_u32_e32 v157, -64, v156
	v_sub_f32_e32 v226, v0, v190
	v_sub_f32_e32 v227, v0, v191
	v_sub_f32_e32 v228, v0, v192
	v_sub_f32_e32 v229, v0, v193
	v_mul_f32_e32 v226, 0x3fb8aa3b, v226
	v_mul_f32_e32 v227, 0x3fb8aa3b, v227
	v_mul_f32_e32 v228, 0x3fb8aa3b, v228
	v_mul_f32_e32 v229, 0x3fb8aa3b, v229
	v_exp_f32_e32 v226, v226
	v_exp_f32_e32 v227, v227
	v_exp_f32_e32 v228, v228
	v_exp_f32_e32 v229, v229
	v_mul_f32_e32 v226, v52, v226
	v_mul_f32_e32 v227, v53, v227
	v_mul_f32_e32 v228, v54, v228
	v_mul_f32_e32 v229, v55, v229
	v_mul_f32_e32 v226, v196, v226
	v_mul_f32_e32 v227, v197, v227
	v_mul_f32_e32 v228, v198, v228
	v_mul_f32_e32 v229, v199, v229
	v_cmp_le_i32_e64 s[10:11], 0, v157
	v_cmp_le_i32_e64 s[30:31], 1, v157
	v_cmp_le_i32_e64 s[100:101], 2, v157
	v_cndmask_b32_e64 v226, 0, v226, s[10:11]
	v_cndmask_b32_e64 v227, 0, v227, s[30:31]
	v_cmp_le_i32_e64 s[10:11], 3, v157
	v_cndmask_b32_e64 v228, 0, v228, s[100:101]
	s_nop 1
	v_cndmask_b32_e64 v229, 0, v229, s[10:11]
	v_cvt_pk_bf16_f32 v230, v226, v227
	v_cvt_pk_bf16_f32 v231, v228, v229
	ds_write_b64 v133, v[230:231] offset:34944
	v_add_u32_e32 v157, -80, v156
	v_sub_f32_e32 v226, v0, v202
	v_sub_f32_e32 v227, v0, v203
	v_sub_f32_e32 v228, v0, v204
	v_sub_f32_e32 v229, v0, v205
	v_mul_f32_e32 v226, 0x3fb8aa3b, v226
	v_mul_f32_e32 v227, 0x3fb8aa3b, v227
	v_mul_f32_e32 v228, 0x3fb8aa3b, v228
	v_mul_f32_e32 v229, 0x3fb8aa3b, v229
	v_exp_f32_e32 v226, v226
	v_exp_f32_e32 v227, v227
	v_exp_f32_e32 v228, v228
	v_exp_f32_e32 v229, v229
	v_mul_f32_e32 v226, v56, v226
	v_mul_f32_e32 v227, v57, v227
	v_mul_f32_e32 v228, v58, v228
	v_mul_f32_e32 v229, v59, v229
	v_mul_f32_e32 v226, v206, v226
	v_mul_f32_e32 v227, v207, v227
	v_mul_f32_e32 v228, v208, v228
	v_mul_f32_e32 v229, v209, v229
	v_cmp_le_i32_e64 s[10:11], 0, v157
	v_cmp_le_i32_e64 s[30:31], 1, v157
	v_cmp_le_i32_e64 s[100:101], 2, v157
	v_cndmask_b32_e64 v226, 0, v226, s[10:11]
	v_cndmask_b32_e64 v227, 0, v227, s[30:31]
	v_cmp_le_i32_e64 s[10:11], 3, v157
	v_cndmask_b32_e64 v228, 0, v228, s[100:101]
	s_nop 1
	v_cndmask_b32_e64 v229, 0, v229, s[10:11]
	v_cvt_pk_bf16_f32 v232, v226, v227
	v_cvt_pk_bf16_f32 v233, v228, v229
	ds_write_b64 v133, v[232:233] offset:34976
	s_cmp_lt_u32 s98, 6
	s_cbranch_scc1 .Ls3m_cd
	v_add_u32_e32 v157, -96, v156
	v_sub_f32_e32 v226, v0, v210
	v_sub_f32_e32 v227, v0, v211
	v_sub_f32_e32 v228, v0, v212
	v_sub_f32_e32 v229, v0, v213
	v_mul_f32_e32 v226, 0x3fb8aa3b, v226
	v_mul_f32_e32 v227, 0x3fb8aa3b, v227
	v_mul_f32_e32 v228, 0x3fb8aa3b, v228
	v_mul_f32_e32 v229, 0x3fb8aa3b, v229
	v_exp_f32_e32 v226, v226
	v_exp_f32_e32 v227, v227
	v_exp_f32_e32 v228, v228
	v_exp_f32_e32 v229, v229
	v_mul_f32_e32 v226, v60, v226
	v_mul_f32_e32 v227, v61, v227
	v_mul_f32_e32 v228, v62, v228
	v_mul_f32_e32 v229, v63, v229
	v_mul_f32_e32 v226, v214, v226
	v_mul_f32_e32 v227, v215, v227
	v_mul_f32_e32 v228, v216, v228
	v_mul_f32_e32 v229, v217, v229
	v_cmp_le_i32_e64 s[10:11], 0, v157
	v_cmp_le_i32_e64 s[30:31], 1, v157
	v_cmp_le_i32_e64 s[100:101], 2, v157
	v_cndmask_b32_e64 v226, 0, v226, s[10:11]
	v_cndmask_b32_e64 v227, 0, v227, s[30:31]
	v_cmp_le_i32_e64 s[10:11], 3, v157
	v_cndmask_b32_e64 v228, 0, v228, s[100:101]
	s_nop 1
	v_cndmask_b32_e64 v229, 0, v229, s[10:11]
	v_cvt_pk_bf16_f32 v230, v226, v227
	v_cvt_pk_bf16_f32 v231, v228, v229
	ds_write_b64 v133, v[230:231] offset:35008
	v_add_u32_e32 v157, -112, v156
	v_sub_f32_e32 v226, v0, v218
	v_sub_f32_e32 v227, v0, v219
	v_sub_f32_e32 v228, v0, v220
	v_sub_f32_e32 v229, v0, v221
	v_mul_f32_e32 v226, 0x3fb8aa3b, v226
	v_mul_f32_e32 v227, 0x3fb8aa3b, v227
	v_mul_f32_e32 v228, 0x3fb8aa3b, v228
	v_mul_f32_e32 v229, 0x3fb8aa3b, v229
	v_exp_f32_e32 v226, v226
	v_exp_f32_e32 v227, v227
	v_exp_f32_e32 v228, v228
	v_exp_f32_e32 v229, v229
	v_mul_f32_e32 v226, v64, v226
	v_mul_f32_e32 v227, v65, v227
	v_mul_f32_e32 v228, v66, v228
	v_mul_f32_e32 v229, v67, v229
	v_mul_f32_e32 v226, v222, v226
	v_mul_f32_e32 v227, v223, v227
	v_mul_f32_e32 v228, v224, v228
	v_mul_f32_e32 v229, v225, v229
	v_cmp_le_i32_e64 s[10:11], 0, v157
	v_cmp_le_i32_e64 s[30:31], 1, v157
	v_cmp_le_i32_e64 s[100:101], 2, v157
	v_cndmask_b32_e64 v226, 0, v226, s[10:11]
	v_cndmask_b32_e64 v227, 0, v227, s[30:31]
	v_cmp_le_i32_e64 s[10:11], 3, v157
	v_cndmask_b32_e64 v228, 0, v228, s[100:101]
	s_nop 1
	v_cndmask_b32_e64 v229, 0, v229, s[10:11]
	v_cvt_pk_bf16_f32 v232, v226, v227
	v_cvt_pk_bf16_f32 v233, v228, v229
	ds_write_b64 v133, v[232:233] offset:35040
.Ls3m_cd:
.LBB0_266:
	s_or_b64 exec, exec, s[28:29]
	s_waitcnt lgkmcnt(0)
	s_barrier
	ds_read_b128 v[154:157], v109
	ds_read_b128 v[170:173], v142
	ds_read_b128 v[174:177], v142 offset:4352
	ds_read_b128 v[178:181], v142 offset:8704
	ds_read_b128 v[182:185], v142 offset:13056
	ds_read_b128 v[158:161], v109 offset:64
	ds_read_b128 v[186:189], v142 offset:64
	ds_read_b128 v[190:193], v142 offset:4416
	ds_read_b128 v[196:199], v142 offset:8768
	ds_read_b128 v[202:205], v142 offset:13120
	v_mul_f32_e32 v0, 0x3fb8aa3b, v0
	v_exp_f32_e32 v0, v0
	s_waitcnt lgkmcnt(5)
	v_mfma_f32_16x16x32_bf16 v[104:107], v[170:173], v[154:157], 0
	v_mfma_f32_16x16x32_bf16 v[100:103], v[174:177], v[154:157], 0
	v_mfma_f32_16x16x32_bf16 v[96:99], v[178:181], v[154:157], 0
	v_mfma_f32_16x16x32_bf16 v[92:95], v[182:185], v[154:157], 0
	ds_read_b128 v[162:165], v109 offset:128
	ds_read_b128 v[206:209], v142 offset:128
	ds_read_b128 v[210:213], v142 offset:4480
	ds_read_b128 v[214:217], v142 offset:8832
	ds_read_b128 v[218:221], v142 offset:13184
	s_waitcnt lgkmcnt(5)
	v_mfma_f32_16x16x32_bf16 v[104:107], v[186:189], v[158:161], v[104:107]
	v_mfma_f32_16x16x32_bf16 v[100:103], v[190:193], v[158:161], v[100:103]
	v_mfma_f32_16x16x32_bf16 v[96:99], v[196:199], v[158:161], v[96:99]
	v_mfma_f32_16x16x32_bf16 v[92:95], v[202:205], v[158:161], v[92:95]
	ds_read_b128 v[166:169], v109 offset:192
	ds_read_b128 v[222:225], v142 offset:192
	ds_read_b128 v[226:229], v142 offset:4544
	ds_read_b128 v[230:233], v142 offset:8896
	ds_read_b128 v[234:237], v142 offset:13248
	s_waitcnt lgkmcnt(5)
	v_mfma_f32_16x16x32_bf16 v[104:107], v[206:209], v[162:165], v[104:107]
	v_mfma_f32_16x16x32_bf16 v[100:103], v[210:213], v[162:165], v[100:103]
	v_mfma_f32_16x16x32_bf16 v[96:99], v[214:217], v[162:165], v[96:99]
	v_mfma_f32_16x16x32_bf16 v[92:95], v[218:221], v[162:165], v[92:95]
	s_waitcnt lgkmcnt(0)
	v_mfma_f32_16x16x32_bf16 v[104:107], v[222:225], v[166:169], v[104:107]
	v_mfma_f32_16x16x32_bf16 v[100:103], v[226:229], v[166:169], v[100:103]
	v_mfma_f32_16x16x32_bf16 v[96:99], v[230:233], v[166:169], v[96:99]
	v_mfma_f32_16x16x32_bf16 v[92:95], v[234:237], v[166:169], v[92:95]
	s_nop 7
	v_pk_mul_f32 v[104:105], v[0:1], v[104:105] op_sel_hi:[0,1]
	v_pk_mul_f32 v[106:107], v[0:1], v[106:107] op_sel_hi:[0,1]
	v_pk_mul_f32 v[100:101], v[0:1], v[100:101] op_sel_hi:[0,1]
	v_pk_mul_f32 v[102:103], v[0:1], v[102:103] op_sel_hi:[0,1]
	v_pk_mul_f32 v[96:97], v[0:1], v[96:97] op_sel_hi:[0,1]
	v_pk_mul_f32 v[98:99], v[0:1], v[98:99] op_sel_hi:[0,1]
	v_pk_mul_f32 v[92:93], v[0:1], v[92:93] op_sel_hi:[0,1]
	v_pk_mul_f32 v[94:95], v[0:1], v[94:95] op_sel_hi:[0,1]
	v_add_u32_e32 v0, v133, v121
	s_and_saveexec_b64 s[28:29], vcc
	s_cbranch_execnz .LBB0_273
	s_or_b64 exec, exec, s[28:29]
	s_and_saveexec_b64 s[28:29], s[4:5]
	s_cbranch_execnz .LBB0_274

.LBB0_271:
	s_or_b64 exec, exec, s[28:29]
	s_cmpk_eq_i32 s33, 0x200
	s_cselect_b32 s10, s41, s40
	s_cmpk_eq_i32 s33, 0x400
	s_cselect_b32 s10, s42, s10
	s_cmpk_eq_i32 s33, 0x600
	s_cselect_b32 s10, s43, s10
	v_lshlrev_b32_e32 v145, 16, v72
	v_lshlrev_b32_e32 v147, 16, v68
	v_and_b32_e32 v68, 0xffff0000, v68
	v_and_b32_e32 v72, 0xffff0000, v72
	v_mov_b32_e32 v0, s10
	v_lshlrev_b32_e32 v148, 16, v69
	v_lshlrev_b32_e32 v146, 16, v73
	v_and_b32_e32 v73, 0xffff0000, v73
	v_and_b32_e32 v69, 0xffff0000, v69
	s_addk_i32 s33, 0x200
	v_fma_f32 v104, v0, v145, v104
	v_mul_f32_e32 v145, 0xbfb8aa3b, v147
	v_exp_f32_e32 v145, v145
	v_fma_f32 v72, v0, v72, v105
	v_fmac_f32_e32 v107, v0, v73
	v_and_b32_e32 v73, 0xffff0000, v70
	v_add_f32_e32 v145, 1.0, v145
	v_rcp_f32_e32 v145, v145
	s_nop 0
	v_mul_f32_e32 v145, v145, v147
	v_mul_f32_e32 v145, v145, v104
	v_mul_f32_e32 v104, 0xbfb8aa3b, v68
	v_exp_f32_e32 v104, v104
	v_fmac_f32_e32 v144, v145, v145
	v_add_f32_e32 v104, 1.0, v104
	v_rcp_f32_e32 v104, v104
	s_nop 0
	v_mul_f32_e32 v68, v104, v68
	v_mul_f32_e32 v147, v68, v72
	v_mul_f32_e32 v72, 0xbfb8aa3b, v148
	v_exp_f32_e32 v72, v72
	v_fma_f32 v68, v0, v146, v106
	v_fmac_f32_e32 v144, v147, v147
	v_add_f32_e32 v72, 1.0, v72
	v_rcp_f32_e32 v72, v72
	s_nop 0
	v_mul_f32_e32 v72, v72, v148
	v_mul_f32_e32 v106, v72, v68
	v_lshlrev_b32_e32 v72, 16, v70
	v_mul_f32_e32 v70, 0xbfb8aa3b, v72
	v_exp_f32_e32 v70, v70
	v_mul_f32_e32 v68, 0xbfb8aa3b, v69
	v_exp_f32_e32 v68, v68
	v_fmac_f32_e32 v144, v106, v106
	v_add_f32_e32 v70, 1.0, v70
	v_rcp_f32_e32 v104, v70
	v_mul_f32_e32 v70, 0xbfb8aa3b, v73
	v_exp_f32_e32 v70, v70
	v_add_f32_e32 v68, 1.0, v68
	v_rcp_f32_e32 v68, v68
	v_add_f32_e32 v70, 1.0, v70
	v_rcp_f32_e32 v105, v70
	v_mul_f32_e32 v68, v68, v69
	v_mul_f32_e32 v107, v68, v107
	v_and_b32_e32 v69, 0xffff0000, v74
	v_lshlrev_b32_e32 v68, 16, v74
	v_pk_fma_f32 v[68:69], v[0:1], v[68:69], v[100:101] op_sel_hi:[0,1,1]
	v_pk_mul_f32 v[72:73], v[104:105], v[72:73]
	v_fmac_f32_e32 v144, v107, v107
	v_pk_mul_f32 v[68:69], v[72:73], v[68:69]
	v_lshlrev_b32_e32 v74, 16, v71
	v_pk_mul_f32 v[72:73], v[68:69], v[68:69]
	s_nop 0
	v_add_f32_e32 v70, v72, v144
	v_add_f32_e32 v100, v73, v70
	v_and_b32_e32 v73, 0xffff0000, v75
	v_lshlrev_b32_e32 v72, 16, v75
	v_and_b32_e32 v75, 0xffff0000, v71
	v_mul_f32_e32 v70, 0xbfb8aa3b, v74
	v_mul_f32_e32 v71, 0xbfb8aa3b, v75
	v_exp_f32_e32 v70, v70
	v_exp_f32_e32 v71, v71
	v_pk_fma_f32 v[72:73], v[0:1], v[72:73], v[102:103] op_sel_hi:[0,1,1]
	v_add_f32_e32 v70, 1.0, v70
	v_add_f32_e32 v71, 1.0, v71
	v_rcp_f32_e32 v70, v70
	v_rcp_f32_e32 v71, v71
	s_nop 0
	v_pk_mul_f32 v[70:71], v[70:71], v[74:75]
	s_nop 0
	v_pk_mul_f32 v[74:75], v[70:71], v[72:73]
	v_cvt_pk_bf16_f32 v72, v68, v69
	v_lshl_add_u64 v[68:69], v[126:127], 0, s[34:35]
	v_pk_mul_f32 v[70:71], v[74:75], v[74:75]
	v_cvt_pk_bf16_f32 v73, v74, v75
	s_add_u32 s34, s34, 0x80
	v_add_f32_e32 v70, v70, v100
	v_add_f32_e32 v100, v71, v70
	v_cvt_pk_bf16_f32 v70, v145, v147
	v_cvt_pk_bf16_f32 v71, v106, v107
	global_store_dwordx4 v[68:69], v[70:73], off offset:-64
	s_addc_u32 s35, s35, 0
	s_add_u32 s38, s38, 4
	v_lshlrev_b32_e32 v70, 16, v28
	v_and_b32_e32 v71, 0xffff0000, v28
	v_mul_f32_e32 v28, 0xbfb8aa3b, v70
	v_exp_f32_e32 v28, v28
	v_and_b32_e32 v73, 0xffff0000, v32
	v_lshlrev_b32_e32 v72, 16, v32
	v_pk_fma_f32 v[72:73], v[0:1], v[72:73], v[96:97] op_sel_hi:[0,1,1]
	v_add_f32_e32 v28, 1.0, v28
	v_rcp_f32_e32 v74, v28
	v_mul_f32_e32 v28, 0xbfb8aa3b, v71
	v_exp_f32_e32 v28, v28
	v_lshlrev_b32_e32 v32, 16, v29
	s_addc_u32 s39, s39, 0
	s_add_i32 s36, s36, 1
	v_add_f32_e32 v28, 1.0, v28
	v_rcp_f32_e32 v75, v28
	s_cmpk_lg_i32 s33, 0x800
	v_pk_mul_f32 v[70:71], v[74:75], v[70:71]
	s_nop 0
	v_pk_mul_f32 v[70:71], v[70:71], v[72:73]
	s_nop 0
	v_pk_mul_f32 v[72:73], v[70:71], v[70:71]
	s_nop 0
	v_add_f32_e32 v28, v72, v100
	v_add_f32_e32 v74, v73, v28
	v_and_b32_e32 v73, 0xffff0000, v33
	v_lshlrev_b32_e32 v72, 16, v33
	v_and_b32_e32 v33, 0xffff0000, v29
	v_mul_f32_e32 v28, 0xbfb8aa3b, v32
	v_mul_f32_e32 v29, 0xbfb8aa3b, v33
	v_exp_f32_e32 v28, v28
	v_exp_f32_e32 v29, v29
	v_pk_fma_f32 v[72:73], v[0:1], v[72:73], v[98:99] op_sel_hi:[0,1,1]
	v_add_f32_e32 v28, 1.0, v28
	v_add_f32_e32 v29, 1.0, v29
	v_rcp_f32_e32 v28, v28
	v_rcp_f32_e32 v29, v29
	s_nop 0
	v_pk_mul_f32 v[28:29], v[28:29], v[32:33]
	s_nop 0
	v_pk_mul_f32 v[32:33], v[28:29], v[72:73]
	v_lshlrev_b32_e32 v72, 16, v30
	v_and_b32_e32 v73, 0xffff0000, v30
	v_mul_f32_e32 v30, 0xbfb8aa3b, v72
	v_exp_f32_e32 v30, v30
	v_pk_mul_f32 v[28:29], v[32:33], v[32:33]
	v_add_f32_e32 v30, 1.0, v30
	v_add_f32_e32 v28, v28, v74
	v_rcp_f32_e32 v74, v30
	v_mul_f32_e32 v30, 0xbfb8aa3b, v73
	v_exp_f32_e32 v30, v30
	v_add_f32_e32 v96, v29, v28
	v_and_b32_e32 v29, 0xffff0000, v34
	v_lshlrev_b32_e32 v28, 16, v34
	v_add_f32_e32 v30, 1.0, v30
	v_rcp_f32_e32 v75, v30
	v_pk_fma_f32 v[28:29], v[0:1], v[28:29], v[92:93] op_sel_hi:[0,1,1]
	v_lshlrev_b32_e32 v34, 16, v31
	v_mul_f32_e32 v30, 0xbfb8aa3b, v34
	v_pk_mul_f32 v[72:73], v[74:75], v[72:73]
	v_exp_f32_e32 v30, v30
	v_pk_mul_f32 v[72:73], v[72:73], v[28:29]
	v_add_f32_e32 v30, 1.0, v30
	v_pk_mul_f32 v[28:29], v[72:73], v[72:73]
	v_rcp_f32_e32 v30, v30
	v_add_f32_e32 v28, v28, v96
	v_add_f32_e32 v74, v29, v28
	v_and_b32_e32 v29, 0xffff0000, v35
	v_lshlrev_b32_e32 v28, 16, v35
	v_and_b32_e32 v35, 0xffff0000, v31
	v_pk_fma_f32 v[28:29], v[0:1], v[28:29], v[94:95] op_sel_hi:[0,1,1]
	v_mul_f32_e32 v0, 0xbfb8aa3b, v35
	v_exp_f32_e32 v0, v0
	s_nop 0
	v_add_f32_e32 v0, 1.0, v0
	v_rcp_f32_e32 v31, v0
	s_nop 0
	v_pk_mul_f32 v[30:31], v[30:31], v[34:35]
	s_nop 0
	v_pk_mul_f32 v[34:35], v[30:31], v[28:29]
	v_cvt_pk_bf16_f32 v30, v72, v73
	s_nop 0
	v_pk_mul_f32 v[28:29], v[34:35], v[34:35]
	v_cvt_pk_bf16_f32 v31, v34, v35
	s_nop 0
	v_add_f32_e32 v0, v28, v74
	v_add_f32_e32 v144, v29, v0
	v_cvt_pk_bf16_f32 v28, v70, v71
	v_cvt_pk_bf16_f32 v29, v32, v33
	global_store_dwordx4 v[68:69], v[28:31], off
	s_waitcnt lgkmcnt(0)
	s_barrier
	s_cbranch_scc0 .LBB0_136
	s_waitcnt vmcnt(2)
	v_mov_b64_e32 v[68:69], v[84:85]
	v_mov_b64_e32 v[70:71], v[86:87]
	v_mov_b64_e32 v[28:29], v[88:89]
	v_mov_b64_e32 v[30:31], v[90:91]
	v_mov_b64_e32 v[72:73], v[76:77]
	v_mov_b64_e32 v[74:75], v[78:79]
	v_mov_b64_e32 v[32:33], v[80:81]
	v_mov_b64_e32 v[34:35], v[82:83]
	s_branch .LBB0_186
	s_nop 0
	s_nop 0
	s_nop 0
	s_nop 0
	s_nop 0
	s_nop 0
	s_nop 0
	s_nop 0
	s_nop 0
	s_nop 0
	s_nop 0
	s_nop 0
	s_nop 0
	s_nop 0
	s_nop 0
	s_nop 0
	s_nop 0
	s_nop 0
